# strategy #9 / asm guide 7.12 (shorten hipcc's wave-uniform ballot): v45 + 5 sites v_cndmask 0,1 + v_cmp_ne 1 -> one s_andn2_b64 (SB and DIFF tile paths, P3/P7 unit headers, P3 epilogue)
# speedup vs baseline: 1.0028x; 1.0021x over previous
.LBB0_318:
	v_exp_f32_e32 v84, v68
	v_exp_f32_e32 v85, v69
	v_exp_f32_e32 v86, v70
	v_exp_f32_e32 v71, v71
	v_add_f32_e32 v68, 0, v84
	v_exp_f32_e32 v72, v72
	v_add_f32_e32 v68, v85, v68
	v_exp_f32_e32 v73, v73
	v_add_f32_e32 v68, v86, v68
	v_exp_f32_e32 v74, v74
	v_add_f32_e32 v68, v71, v68
	v_exp_f32_e32 v75, v75
	v_add_f32_e32 v68, v72, v68
	v_exp_f32_e32 v76, v76
	v_add_f32_e32 v68, v73, v68
	v_exp_f32_e32 v77, v77
	v_add_f32_e32 v68, v74, v68
	v_exp_f32_e32 v78, v78
	v_add_f32_e32 v68, v75, v68
	v_exp_f32_e32 v79, v79
	v_add_f32_e32 v68, v76, v68
	v_exp_f32_e32 v80, v80
	v_add_f32_e32 v68, v77, v68
	v_exp_f32_e32 v81, v81
	v_add_f32_e32 v68, v78, v68
	v_exp_f32_e32 v82, v82
	v_add_f32_e32 v68, v79, v68
	v_exp_f32_e32 v83, v83
	v_add_f32_e32 v68, v80, v68
	v_exp_f32_e32 v52, v52
	v_add_f32_e32 v68, v81, v68
	v_exp_f32_e32 v53, v53
	v_add_f32_e32 v68, v82, v68
	v_exp_f32_e32 v54, v54
	v_add_f32_e32 v68, v83, v68
	v_exp_f32_e32 v55, v55
	v_add_f32_e32 v68, v52, v68
	v_exp_f32_e32 v56, v56
	v_add_f32_e32 v68, v53, v68
	v_exp_f32_e32 v57, v57
	v_add_f32_e32 v68, v54, v68
	v_exp_f32_e32 v58, v58
	v_add_f32_e32 v68, v55, v68
	v_exp_f32_e32 v59, v59
	v_add_f32_e32 v68, v56, v68
	v_exp_f32_e32 v60, v60
	v_add_f32_e32 v68, v57, v68
	v_exp_f32_e32 v61, v61
	v_add_f32_e32 v68, v58, v68
	v_exp_f32_e32 v62, v62
	v_add_f32_e32 v68, v59, v68
	v_exp_f32_e32 v63, v63
	v_exp_f32_e32 v64, v64
	v_exp_f32_e32 v65, v65
	v_exp_f32_e32 v66, v66
	v_exp_f32_e32 v67, v67
	v_cvt_pk_bf16_f32 v70, v84, v85
	v_cvt_pk_bf16_f32 v71, v86, v71
	v_cvt_pk_bf16_f32 v72, v72, v73
	v_cvt_pk_bf16_f32 v73, v74, v75
	v_cvt_pk_bf16_f32 v74, v76, v77
	v_cvt_pk_bf16_f32 v75, v78, v79
	v_cvt_pk_bf16_f32 v76, v80, v81
	v_cvt_pk_bf16_f32 v77, v82, v83
	v_cvt_pk_bf16_f32 v78, v52, v53
	v_cvt_pk_bf16_f32 v79, v54, v55
	v_cvt_pk_bf16_f32 v80, v56, v57
	v_cvt_pk_bf16_f32 v81, v58, v59
	v_cvt_pk_bf16_f32 v118, v60, v61
	v_cvt_pk_bf16_f32 v119, v62, v63
	v_cvt_pk_bf16_f32 v120, v64, v65
	v_cvt_pk_bf16_f32 v121, v66, v67
	ds_read_b64_tr_b16 v[82:83], v236 offset:0
	v_add_f32_e32 v68, v60, v68
	ds_read_b64_tr_b16 v[84:85], v236 offset:0x800
	v_add_f32_e32 v68, v61, v68
	ds_read_b64_tr_b16 v[86:87], v236 offset:0x1000
	v_add_f32_e32 v68, v62, v68
	ds_read_b64_tr_b16 v[88:89], v236 offset:0x1800
	v_add_f32_e32 v68, v63, v68
	ds_read_b64_tr_b16 v[90:91], v236 offset:0x2000
	v_add_f32_e32 v68, v64, v68
	ds_read_b64_tr_b16 v[92:93], v236 offset:0x2800
	v_add_f32_e32 v68, v65, v68
	ds_read_b64_tr_b16 v[94:95], v236 offset:0x3000
	v_add_f32_e32 v68, v66, v68
	ds_read_b64_tr_b16 v[96:97], v236 offset:0x3800
	v_add_f32_e32 v68, v67, v68
	s_waitcnt lgkmcnt(0)
	v_mov_b32_e32 v69, v68
	s_nop 1
	v_permlane32_swap_b32_e32 v68, v69
	v_permlane32_swap_b32_e32 v70, v72
	v_permlane32_swap_b32_e32 v71, v73
	v_permlane32_swap_b32_e32 v74, v76
	v_permlane32_swap_b32_e32 v75, v77
	v_permlane32_swap_b32_e32 v78, v80
	v_permlane32_swap_b32_e32 v79, v81
	v_permlane32_swap_b32_e32 v118, v120
	v_permlane32_swap_b32_e32 v119, v121
	v_mfma_f32_32x32x16_bf16 v[52:67], v[70:73], v[82:85], v[36:51]
	ds_read_b64_tr_b16 v[100:101], v236 offset:0x200
	ds_read_b64_tr_b16 v[102:103], v236 offset:0xa00
	ds_read_b64_tr_b16 v[104:105], v236 offset:0x1200
	ds_read_b64_tr_b16 v[106:107], v236 offset:0x1a00
	ds_read_b64_tr_b16 v[108:109], v236 offset:0x2200
	ds_read_b64_tr_b16 v[110:111], v236 offset:0x2a00
	ds_read_b64_tr_b16 v[112:113], v236 offset:0x3200
	v_mfma_f32_32x32x16_bf16 v[52:67], v[74:77], v[86:89], v[52:67]
	ds_read_b64_tr_b16 v[114:115], v236 offset:0x3a00
	s_waitcnt lgkmcnt(0)
	v_mfma_f32_32x32x16_bf16 v[52:67], v[78:81], v[90:93], v[52:67]
	v_mfma_f32_32x32x16_bf16 v[52:67], v[118:121], v[94:97], v[52:67]
	v_mfma_f32_32x32x16_bf16 v[84:99], v[70:73], v[100:103], v[36:51]
	ds_read_b64_tr_b16 v[122:123], v236 offset:0x400
	ds_read_b64_tr_b16 v[124:125], v236 offset:0xc00
	ds_read_b64_tr_b16 v[126:127], v236 offset:0x1400
	ds_read_b64_tr_b16 v[128:129], v236 offset:0x1c00
	ds_read_b64_tr_b16 v[148:149], v236 offset:0x2400
	ds_read_b64_tr_b16 v[150:151], v236 offset:0x2c00
	ds_read_b64_tr_b16 v[158:159], v236 offset:0x3400
	v_mfma_f32_32x32x16_bf16 v[84:99], v[74:77], v[104:107], v[84:99]
	ds_read_b64_tr_b16 v[160:161], v236 offset:0x3c00
	s_waitcnt lgkmcnt(0)
	v_mfma_f32_32x32x16_bf16 v[84:99], v[78:81], v[108:111], v[84:99]
	v_mfma_f32_32x32x16_bf16 v[84:99], v[118:121], v[112:115], v[84:99]
	v_mfma_f32_32x32x16_bf16 v[100:115], v[70:73], v[122:125], v[36:51]
	ds_read_b64_tr_b16 v[122:123], v236 offset:0x600
	ds_read_b64_tr_b16 v[124:125], v236 offset:0xe00
	v_mfma_f32_32x32x16_bf16 v[100:115], v[74:77], v[126:129], v[100:115]
	ds_read_b64_tr_b16 v[126:127], v236 offset:0x1600
	ds_read_b64_tr_b16 v[128:129], v236 offset:0x1e00
	v_mfma_f32_32x32x16_bf16 v[100:115], v[78:81], v[148:151], v[100:115]
	ds_read_b64_tr_b16 v[148:149], v236 offset:0x2600
	ds_read_b64_tr_b16 v[150:151], v236 offset:0x2e00
	v_mfma_f32_32x32x16_bf16 v[100:115], v[118:121], v[158:161], v[100:115]
	ds_read_b64_tr_b16 v[158:159], v236 offset:0x3600
	ds_read_b64_tr_b16 v[160:161], v236 offset:0x3e00
	s_waitcnt lgkmcnt(0)
	v_mfma_f32_32x32x16_bf16 v[36:51], v[70:73], v[122:125], v[36:51]
	s_andn2_b64 s[42:43], exec, s[8:9]
	s_andn2_b64 vcc, exec, s[8:9]
	v_mfma_f32_32x32x16_bf16 v[36:51], v[74:77], v[126:129], v[36:51]
	v_mfma_f32_32x32x16_bf16 v[36:51], v[78:81], v[148:151], v[36:51]
	v_mfma_f32_32x32x16_bf16 v[36:51], v[118:121], v[158:161], v[36:51]
	s_cbranch_vccnz .LBB0_320
	v_add_u32_e32 v70, s88, v153
	s_waitcnt vmcnt(2)
	ds_write_b128 v70, v[132:135] offset:32768
	v_add_u32_e32 v70, s89, v224
	s_waitcnt vmcnt(1)
	ds_write_b128 v70, v[136:139]
	v_add_u32_e32 v70, s89, v225
	s_waitcnt vmcnt(0)
	ds_write_b128 v70, v[140:143]

.LBB0_669:
	v_pk_mul_f32 v[40:41], v[84:85], s[4:5] op_sel_hi:[1,0]
	v_pk_mul_f32 v[42:43], v[100:101], s[4:5] op_sel_hi:[1,0]
	v_exp_f32_e64 v46, -|v40|
	v_exp_f32_e64 v47, -|v41|
	v_exp_f32_e64 v48, -|v42|
	v_exp_f32_e64 v49, -|v43|
	v_max_f32_e32 v84, 0, v40
	v_pk_add_f32 v[46:47], v[46:47], 1.0 op_sel_hi:[1,0]
	v_max_f32_e32 v85, 0, v41
	v_pk_add_f32 v[48:49], v[48:49], 1.0 op_sel_hi:[1,0]
	v_log_f32_e32 v46, v46
	v_log_f32_e32 v47, v47
	v_log_f32_e32 v48, v48
	v_log_f32_e32 v49, v49
	v_pk_add_f32 v[164:165], v[84:85], v[46:47]
	v_max_f32_e32 v46, 0, v42
	v_max_f32_e32 v47, 0, v43
	v_pk_add_f32 v[166:167], v[46:47], v[48:49]
	s_andn2_b64 s[42:43], exec, s[48:49]
	s_andn2_b64 vcc, exec, s[48:49]
	s_cbranch_vccz .Lsbd_670

.LBB0_899:
	s_mul_i32 s65, s20, -6
	s_add_i32 s65, s65, s64
	s_andn2_b64 s[38:39], exec, s[40:41]
	s_andn2_b64 vcc, exec, s[40:41]
	s_mov_b64 s[46:47], s[22:23]
	s_cbranch_vccnz .LBB0_903
	s_bitcmp1_b32 s9, 0
	s_cselect_b64 s[18:19], -1, 0
	s_and_b64 vcc, exec, s[18:19]
	v_readlane_b32 s18, v254, 38
	v_readlane_b32 s19, v254, 39
	s_cbranch_vccnz .LBB0_902
	s_ashr_i32 s18, s65, 1
	s_cmp_gt_i32 s18, 0
	s_cselect_b32 s19, 0x600, 0
	s_cmp_gt_i32 s18, 1
	s_cselect_b32 s18, 0x500, 0
	v_readlane_b32 s20, v252, 59
	s_add_u32 s18, s20, s18
	v_readlane_b32 s20, v252, 60
	s_addc_u32 s20, s20, 0
	s_add_u32 s18, s18, s19
	s_addc_u32 s19, s20, 0

.LBB0_916:
	s_andn2_b64 s[40:41], exec, s[8:9]
	s_andn2_b64 vcc, exec, s[8:9]
	v_mov_b32_e32 v153, 0
	v_mov_b32_e32 v154, 0
	v_mov_b32_e32 v155, 0
	s_cbranch_vccnz .LBB0_918
	global_load_dwordx4 v[152:155], v[132:133], off offset:256

.LBB0_1190:
	s_andn2_b64 s[38:39], exec, s[40:41]
	s_andn2_b64 vcc, exec, s[40:41]
	s_mov_b64 s[44:45], s[8:9]
	s_cbranch_vccnz .LBB0_1192
	s_mul_i32 s21, s56, 0x2c0000
	v_readlane_b32 s22, v255, 5
	s_mul_hi_i32 s20, s56, 0x2c0000
	v_readlane_b32 s23, v255, 6
	s_add_u32 s44, s22, s21
	s_addc_u32 s45, s23, s20
